# v91 plus grid-size guards (fallback to original scheduling if grid != 256 WGs)
# speedup vs baseline: 1.0061x; 1.0052x over previous
; #define LAS __attribute__((address_space(3)))
; __device__ __forceinline__ unsigned pk2(float lo, float hi) { unsigned r; asm("v_cvt_pk_bf16_f32 %0, %1, %2" : "=v"(r) : "v"(lo), "v"(hi)); return r; }
; __device__ __forceinline__ void lds_fence() { asm volatile("s_waitcnt lgkmcnt(0)" ::: "memory"); }
; __device__ __forceinline__ float log2_gamma(int h) { return log2f(1.0f - exp2f(-5.0f - (float)h)); }
; __device__ __forceinline__ void retout_item(const bf16_t* hbuf, const float* rot, const float* kvbuf, const float* normg, bf16_t* mixed, LAS bf16_t* vT, int item, int lane) {
;     const int bh = item / NCHUNK, n = item % NCHUNK, b = bh / 6, h = bh % 6; const size_t t0 = (size_t)b * SEQ + (size_t)n * 64;
;     const int r = lane & 15, q = lane >> 4; const float l2g = log2_gamma(h);
;     load_tile_T<false>(hbuf + t0 * INWP + C_RV + h * 64, vT, lane, 0.f, 0.f);
;     const float* cs = rot; const float* sn = rot + 16384 * 32;
;     bf16x8 kf[4][2]; LAS bf16_t* RT = vT + 64 * TLD;
; #pragma unroll
;     for (int mt = 0; mt < 4; ++mt) { const int row = 16 * mt + r; const bf16_t* kp = hbuf + (t0 + row) * INWP + C_RK + h * 64 + 8 * q; const int pos = n * 64 + row; u32x4 o1, o2;
;         rot8(*(const u32x4*)kp, *(const u32x4*)(kp + 32), cs + (size_t)pos * 32 + 8 * q, sn + (size_t)pos * 32 + 8 * q, 0.125f, o1, o2); kf[mt][0] = as_bf16x8(o1); kf[mt][1] = as_bf16x8(o2); }
;     const float* Rp = kvbuf + (size_t)item * 4096;
; #pragma unroll
;     for (int et = 0; et < 4; ++et)
; #pragma unroll
;         for (int ks = 0; ks < 2; ++ks) { const float* p = Rp + (16 * et + r) * 64 + 32 * ks + 8 * q; const f32x4 a = *(const f32x4*)p, c = *(const f32x4*)(p + 4);
;             *(LAS u32x4*)(RT + (16 * et + r) * TLD + 32 * ks + 8 * q) = (u32x4){pk2(a[0], a[1]), pk2(a[2], a[3]), pk2(c[0], c[1]), pk2(c[2], c[3])}; }
;     lds_fence();
; #pragma unroll 1
;     for (int ct = 0; ct < 4; ++ct) {
;         const int c = 16 * ct + r; const bf16_t* qp = hbuf + (t0 + c) * INWP + C_RQ + h * 64 + 8 * q; const int pos = n * 64 + c; u32x4 o1, o2;
.LBB0_170:
	s_ashr_i32 s15, s71, 6
	v_readlane_b32 s12, v251, 16
	s_add_i32 s16, s15, s12
	v_readlane_b32 s98, v254, 48
	s_lshr_b32 s99, s12, 1
	s_and_b32 s100, s15, 3
	s_add_i32 s99, s99, s100
	s_lshr_b32 s100, s15, 2
	s_lshl_b32 s100, s100, 10
	s_add_i32 s99, s99, s100
	s_cmp_eq_u32 s98, 1
	s_cselect_b32 s99, s99, s16
	v_readlane_b32 s98, v249, 49
	s_nop 0
	s_cmp_eq_u32 s98, 0x100
	s_cselect_b32 s16, s99, s16
	s_and_b64 vcc, exec, s[0:1]
	v_writelane_b32 v249, s15, 52
	s_cbranch_vccz .LBB0_352
	v_readlane_b32 s0, v254, 48
	s_cmp_gt_i32 s0, 1
	s_mov_b64 s[0:1], -1
	s_cbranch_scc0 .LBB0_322
	v_readlane_b32 s0, v254, 48
	s_cmp_gt_i32 s0, 2
	s_mov_b64 s[0:1], -1
	s_cbranch_scc0 .LBB0_179
	s_cmpk_gt_i32 s16, 0xbff
	s_cbranch_scc1 .LBB0_178
	v_lshrrev_b32_e32 v1, 4, v248
	v_readlane_b32 s20, v251, 19
	v_lshlrev_b32_e32 v32, 5, v1
	v_readlane_b32 s21, v251, 20
	v_readlane_b32 s0, v249, 52
	s_mulk_i32 s0, 0x4800
	s_waitcnt vmcnt(0)
	v_lshl_add_u64 v[64:65], s[20:21], 0, v[32:33]
	v_readlane_b32 s20, v251, 59
	v_readlane_b32 s21, v251, 60
	v_lshrrev_b32_e32 v3, 3, v248
	v_and_b32_e32 v4, 7, v168
	v_lshl_add_u64 v[66:67], s[20:21], 0, v[32:33]
	v_readlane_b32 s20, v251, 57
	v_readlane_b32 s21, v251, 58
	s_add_i32 s0, s0, 0
	v_lshlrev_b32_e32 v0, 3, v4
	v_mul_u32_u24_e32 v2, 0xc00, v3
	v_mul_u32_u24_e32 v4, 0x480, v4
	v_lshlrev_b32_e32 v3, 1, v3
	v_lshlrev_b32_e32 v62, 3, v1
	v_lshl_add_u64 v[74:75], s[20:21], 0, v[32:33]
	v_and_b32_e32 v32, 48, v248
	v_lshlrev_b32_e32 v61, 2, v1
	v_lshlrev_b32_e32 v1, 2, v248
	v_and_b32_e32 v60, 15, v168
	v_add3_u32 v39, s0, v4, v3
	v_or_b32_e32 v72, 48, v248
	v_add_u32_e32 v3, s0, v32
	v_xor_b32_e32 v69, 64, v1
	v_xor_b32_e32 v71, 0x80, v1
	v_mov_b32_e32 v1, s0
	s_movk_i32 s0, 0x90
	v_mad_u32_u24 v73, v60, s0, v1
	v_mad_u32_u24 v109, v72, s0, v1
	v_readlane_b32 s0, v249, 5
	v_readlane_b32 s1, v249, 6
	v_mov_b32_e32 v63, v33
	v_or_b32_e32 v68, 16, v60
	v_lshl_add_u64 v[76:77], s[0:1], 0, v[32:33]
	v_readlane_b32 s0, v253, 38
	v_readlane_b32 s1, v253, 39
	v_or_b32_e32 v70, 32, v60
	v_add_u32_e32 v105, 0x900, v73
	v_add_u32_e32 v107, 0x1200, v73
	v_lshl_add_u64 v[78:79], s[0:1], 0, v[62:63]
	v_readlane_b32 s44, v251, 0
	v_readlane_b32 s0, v253, 40
	v_lshlrev_b32_e32 v4, 6, v60
	v_mul_u32_u24_e32 v5, 0x90, v60
	v_lshlrev_b32_e32 v6, 6, v68
	v_lshlrev_b32_e32 v8, 6, v70
	v_lshlrev_b32_e32 v10, 6, v72
	v_mul_u32_u24_e32 v7, 0x90, v72
	v_add_u32_e32 v104, v73, v32
	v_add_u32_e32 v106, v105, v32
	v_add_u32_e32 v108, v107, v32
	v_add_u32_e32 v110, v109, v32
	v_sub_u32_e32 v1, v61, v60
	v_and_b32_e32 v32, 48, v168
	v_readlane_b32 s50, v251, 6
	v_readlane_b32 s51, v251, 7
	v_readlane_b32 s1, v253, 41
	v_or_b32_e32 v111, 1, v61
	v_or_b32_e32 v112, 2, v61
	v_or_b32_e32 v113, 3, v61
	v_or_b32_e32 v114, 16, v61
	v_or_b32_e32 v115, 17, v61
	v_or_b32_e32 v116, 18, v61
	v_or_b32_e32 v117, 19, v61
	v_or_b32_e32 v118, 32, v61
	v_or_b32_e32 v119, 33, v61
	v_or_b32_e32 v120, 34, v61
	v_or_b32_e32 v121, 35, v61
	v_or_b32_e32 v122, 48, v61
	v_or_b32_e32 v123, 49, v61
	v_or_b32_e32 v124, 50, v61
	v_or_b32_e32 v125, 51, v61
	v_add_u32_e32 v126, 51, v1
	v_sub_u32_e32 v127, v60, v61
	v_lshl_add_u64 v[80:81], s[50:51], 0, v[32:33]
	v_lshl_add_u64 v[82:83], s[0:1], 0, v[62:63]
	v_lshlrev_b32_e32 v32, 1, v0
	v_lshlrev_b32_e32 v84, 1, v2
	v_lshlrev_b32_e32 v86, 1, v62
	v_lshlrev_b32_e32 v88, 2, v4
	v_add_u32_e32 v63, v3, v5
	v_lshlrev_b32_e32 v90, 2, v6
	v_lshlrev_b32_e32 v92, 2, v8
	v_lshlrev_b32_e32 v94, 2, v10
	v_add_u32_e32 v128, v3, v7
	s_mov_b32 s0, s16
	v_readlane_b32 s45, v251, 1
	v_readlane_b32 s46, v251, 2
	v_readlane_b32 s47, v251, 3
	v_readlane_b32 s48, v251, 4
	v_readlane_b32 s49, v251, 5

; #define LAS __attribute__((address_space(3)))
; __device__ __forceinline__ unsigned pk2(float lo, float hi) { unsigned r; asm("v_cvt_pk_bf16_f32 %0, %1, %2" : "=v"(r) : "v"(lo), "v"(hi)); return r; }
; __device__ __forceinline__ void rot8(u32x4 x1, u32x4 x2, const float* cs, const float* sn, float sc, u32x4& o1, u32x4& o2) {
;     const f32x4 c0 = *(const f32x4*)cs, c1 = *(const f32x4*)(cs + 4), s0 = *(const f32x4*)sn, s1 = *(const f32x4*)(sn + 4);
;     float a[8], b[8], c[8], s[8];
;     a[0] = bflo(x1.x); a[1] = bfhi(x1.x); a[2] = bflo(x1.y); a[3] = bfhi(x1.y); a[4] = bflo(x1.z); a[5] = bfhi(x1.z); a[6] = bflo(x1.w); a[7] = bfhi(x1.w);
;     b[0] = bflo(x2.x); b[1] = bfhi(x2.x); b[2] = bflo(x2.y); b[3] = bfhi(x2.y); b[4] = bflo(x2.z); b[5] = bfhi(x2.z); b[6] = bflo(x2.w); b[7] = bfhi(x2.w);
; #pragma unroll
;     for (int i = 0; i < 4; ++i) { c[i] = c0[i]; c[4 + i] = c1[i]; s[i] = s0[i]; s[4 + i] = s1[i]; }
;     float p[8], q[8];
; #pragma unroll
;     for (int i = 0; i < 8; ++i) { p[i] = (a[i] * c[i] - b[i] * s[i]) * sc; q[i] = (a[i] * s[i] + b[i] * c[i]) * sc; }
;     o1.x = pk2(p[0], p[1]); o1.y = pk2(p[2], p[3]); o1.z = pk2(p[4], p[5]); o1.w = pk2(p[6], p[7]);
;     o2.x = pk2(q[0], q[1]); o2.y = pk2(q[2], q[3]); o2.z = pk2(q[4], q[5]); o2.w = pk2(q[6], q[7]);
; __device__ __forceinline__ void retout_item(const bf16_t* hbuf, const float* rot, const float* kvbuf, const float* normg, bf16_t* mixed, LAS bf16_t* vT, int item, int lane) {
;     ...
;     for (int ct = 0; ct < 4; ++ct) {
;         const int c = 16 * ct + r; const bf16_t* qp = hbuf + (t0 + c) * INWP + C_RQ + h * 64 + 8 * q; const int pos = n * 64 + c; u32x4 o1, o2;
;         rot8(*(const u32x4*)qp, *(const u32x4*)(qp + 32), cs + (size_t)pos * 32 + 8 * q, sn + (size_t)pos * 32 + 8 * q, 1.0f, o1, o2);
;         const bf16x8 q0 = as_bf16x8(o1), q1 = as_bf16x8(o2);
;         f32x4 OT[4];
;         const float xi = __builtin_amdgcn_exp2f(l2g * (float)(c + 1));
; #pragma unroll
;         for (int et = 0; et < 4; ++et) { f32x4 acc = {0.f, 0.f, 0.f, 0.f};
;             const bf16x8 R0 = *(const LAS bf16x8*)(RT + (16 * et + r) * TLD + 8 * q), R1 = *(const LAS bf16x8*)(RT + (16 * et + r) * TLD + 32 + 8 * q);
;             acc = __builtin_amdgcn_mfma_f32_16x16x32_bf16(R0, q0, acc, 0, 0, 0); acc = __builtin_amdgcn_mfma_f32_16x16x32_bf16(R1, q1, acc, 0, 0, 0);
;             OT[et] = acc * xi; }
.LBB0_176:
	v_add_u32_e32 v44, s12, v87
	v_lshl_add_u64 v[34:35], v[100:101], 0, s[36:37]
	v_ashrrev_i32_e32 v45, 31, v44
	v_add_co_u32_e32 v40, vcc, 0x1d408000, v34
	v_lshlrev_b64 v[44:45], 7, v[44:45]
	s_nop 0
	v_addc_co_u32_e32 v41, vcc, 0, v35, vcc
	v_lshl_add_u64 v[48:49], v[64:65], 0, v[44:45]
	v_lshl_add_u64 v[56:57], v[66:67], 0, v[44:45]
	global_load_dwordx4 v[34:37], v[40:41], off offset:2816
	s_nop 0
	global_load_dwordx4 v[40:43], v[40:41], off offset:2880
	s_nop 0
	global_load_dwordx4 v[44:47], v[48:49], off offset:16
	s_nop 0
	global_load_dwordx4 v[48:51], v[48:49], off
	s_nop 0
	global_load_dwordx4 v[52:55], v[56:57], off offset:16
	s_nop 0
	global_load_dwordx4 v[56:59], v[56:57], off
	v_add_u32_e32 v93, s12, v60
	v_cmp_gt_u32_e32 vcc, v93, v61
	v_subrev_u32_e32 v141, 19, v91
	s_mov_b64 s[20:21], 0x8000
	v_lshl_add_u64 v[100:101], v[100:101], 0, s[10:11]
	s_waitcnt vmcnt(5)
	v_lshlrev_b32_e32 v131, 16, v34
	s_waitcnt vmcnt(4)
	v_lshlrev_b32_e32 v130, 16, v40
	s_waitcnt vmcnt(0)
	v_mov_b32_e32 v132, v56
	v_mov_b32_e32 v133, v48
	v_pk_mul_f32 v[132:133], v[132:133], v[130:131]
	s_nop 0
	v_sub_f32_e32 v89, v133, v132
	v_mov_b32_e32 v132, v48
	v_mov_b32_e32 v133, v56
	v_pk_mul_f32 v[130:131], v[132:133], v[130:131]
	v_mov_b32_e32 v48, v57
	v_add_f32_e32 v95, v130, v131
	v_and_b32_e32 v131, 0xffff0000, v34
	v_and_b32_e32 v130, 0xffff0000, v40
	v_mov_b32_e32 v56, v49
	v_pk_mul_f32 v[132:133], v[48:49], v[130:131]
	v_pk_mul_f32 v[48:49], v[56:57], v[130:131]
	v_mov_b32_e32 v56, v58
	v_add_f32_e32 v130, v48, v49
	v_lshlrev_b32_e32 v49, 16, v35
	v_lshlrev_b32_e32 v48, 16, v41
	v_mov_b32_e32 v57, v50
	v_pk_mul_f32 v[56:57], v[56:57], v[48:49]
	v_and_b32_e32 v35, 0xffff0000, v35
	v_sub_f32_e32 v131, v57, v56
	v_mov_b32_e32 v56, v50
	v_mov_b32_e32 v57, v58
	v_and_b32_e32 v34, 0xffff0000, v41
	v_mov_b32_e32 v50, v59
	v_mov_b32_e32 v58, v51
	v_pk_mul_f32 v[48:49], v[56:57], v[48:49]
	v_pk_mul_f32 v[40:41], v[50:51], v[34:35]
	v_pk_mul_f32 v[34:35], v[58:59], v[34:35]
	v_add_f32_e32 v48, v48, v49
	v_sub_f32_e32 v49, v41, v40
	v_add_f32_e32 v50, v34, v35
	v_lshlrev_b32_e32 v35, 16, v36
	v_lshlrev_b32_e32 v34, 16, v42
	v_mov_b32_e32 v40, v52
	v_mov_b32_e32 v41, v44
	v_pk_mul_f32 v[40:41], v[40:41], v[34:35]
	v_sub_f32_e32 v129, v133, v132
	v_sub_f32_e32 v51, v41, v40
	v_mov_b32_e32 v40, v44
	v_mov_b32_e32 v41, v52
	v_pk_mul_f32 v[34:35], v[40:41], v[34:35]
	v_mov_b32_e32 v44, v53
	v_add_f32_e32 v56, v34, v35
	v_and_b32_e32 v35, 0xffff0000, v36
	v_and_b32_e32 v34, 0xffff0000, v42
	v_mov_b32_e32 v52, v45
	v_pk_mul_f32 v[40:41], v[44:45], v[34:35]
	v_pk_mul_f32 v[34:35], v[52:53], v[34:35]
	v_sub_f32_e32 v42, v41, v40
	v_add_f32_e32 v44, v34, v35
	v_lshlrev_b32_e32 v35, 16, v37
	v_lshlrev_b32_e32 v34, 16, v43
	v_mov_b32_e32 v40, v54
	v_mov_b32_e32 v41, v46
	v_pk_mul_f32 v[40:41], v[40:41], v[34:35]
	s_nop 0
	v_sub_f32_e32 v45, v41, v40
	v_mov_b32_e32 v40, v46
	v_mov_b32_e32 v41, v54
	v_pk_mul_f32 v[34:35], v[40:41], v[34:35]
	v_mov_b32_e32 v46, v55
	v_add_f32_e32 v52, v34, v35
	v_and_b32_e32 v35, 0xffff0000, v37
	v_and_b32_e32 v34, 0xffff0000, v43
	v_mov_b32_e32 v54, v47
	v_pk_mul_f32 v[36:37], v[46:47], v[34:35]
	v_pk_mul_f32 v[34:35], v[54:55], v[34:35]
	v_sub_f32_e32 v37, v37, v36
	v_add_f32_e32 v43, v34, v35
	v_cvt_pk_bf16_f32 v35, v131, v49
	v_cvt_pk_bf16_f32 v36, v51, v42
	v_cvt_pk_bf16_f32 v41, v48, v50
	v_cvt_pk_bf16_f32 v43, v52, v43
	ds_read_b128 v[46:49], v104 offset:9216
	ds_read_b128 v[50:53], v104 offset:9280
	v_cvt_pk_bf16_f32 v42, v56, v44
	v_add_u32_e32 v44, 1, v93
	v_cvt_f32_u32_e32 v44, v44
	v_cvt_pk_bf16_f32 v34, v89, v129
	v_cvt_pk_bf16_f32 v37, v45, v37
	v_cvt_pk_bf16_f32 v40, v95, v130
	v_mul_f32_e32 v44, v85, v44
	s_waitcnt lgkmcnt(1)
	v_mfma_f32_16x16x32_bf16 v[46:49], v[46:49], v[34:37], 0
	v_exp_f32_e32 v44, v44
	v_add_u32_e32 v129, s12, v127
	v_subrev_u32_e32 v89, 51, v91
	s_waitcnt lgkmcnt(0)
	v_mfma_f32_16x16x32_bf16 v[46:49], v[50:53], v[40:43], v[46:49]
	v_cndmask_b32_e32 v89, v89, v129, vcc
	v_cvt_f32_u32_e32 v89, v89
	v_cmp_gt_u32_e32 vcc, v93, v111
	s_add_i32 s12, s12, 16
	s_cmp_lg_u32 s12, 64
	s_nop 2
	v_pk_mul_f32 v[58:59], v[44:45], v[48:49] op_sel_hi:[0,1]
	v_pk_mul_f32 v[56:57], v[44:45], v[46:47] op_sel_hi:[0,1]
	ds_read_b128 v[46:49], v106 offset:9216
	ds_read_b128 v[50:53], v106 offset:9280
	s_waitcnt lgkmcnt(1)
	v_mfma_f32_16x16x32_bf16 v[46:49], v[46:49], v[34:37], 0
	v_mul_f32_e32 v89, v85, v89
	v_exp_f32_e32 v89, v89
	s_waitcnt lgkmcnt(0)
	v_mfma_f32_16x16x32_bf16 v[46:49], v[50:53], v[40:43], v[46:49]
	s_nop 7
	v_pk_mul_f32 v[54:55], v[44:45], v[48:49] op_sel_hi:[0,1]
	v_pk_mul_f32 v[52:53], v[44:45], v[46:47] op_sel_hi:[0,1]
	ds_read_b128 v[46:49], v108 offset:9216
	ds_read_b128 v[130:133], v108 offset:9280
	s_waitcnt lgkmcnt(1)
	v_mfma_f32_16x16x32_bf16 v[46:49], v[46:49], v[34:37], 0
	s_waitcnt lgkmcnt(0)
	v_mfma_f32_16x16x32_bf16 v[46:49], v[130:133], v[40:43], v[46:49]
	ds_read_b128 v[130:133], v110 offset:9216
	ds_read_b128 v[134:137], v110 offset:9280
	s_waitcnt lgkmcnt(1)
	v_mfma_f32_16x16x32_bf16 v[130:133], v[130:133], v[34:37], 0
	s_nop 3
	v_mul_f32_e64 v50, v44, v48
	v_mul_f32_e64 v51, v44, v49
	v_pk_mul_f32 v[48:49], v[44:45], v[46:47] op_sel_hi:[0,1]
	s_waitcnt lgkmcnt(0)
; __device__ __forceinline__ bf16x8 pack_tiles(const f32x4& t0, const f32x4& t1) { u32x4 w; w.x = pk2(t0[0], t0[1]); w.y = pk2(t0[2], t0[3]); w.z = pk2(t1[0], t1[1]); w.w = pk2(t1[2], t1[3]); return as_bf16x8(w); }
; __device__ __forceinline__ void retout_item(const bf16_t* hbuf, const float* rot, const float* kvbuf, const float* normg, bf16_t* mixed, LAS bf16_t* vT, int item, int lane) {
;     ...
;         f32x4 st[4];
; #pragma unroll
;         for (int mt = 0; mt < 4; ++mt) { f32x4 acc = {0.f, 0.f, 0.f, 0.f};
;             acc = __builtin_amdgcn_mfma_f32_16x16x32_bf16(kf[mt][0], q0, acc, 0, 0, 0); acc = __builtin_amdgcn_mfma_f32_16x16x32_bf16(kf[mt][1], q1, acc, 0, 0, 0);
; #pragma unroll
;             for (int j = 0; j < 4; ++j) { const int m = 16 * mt + 4 * q + j; const int dd = c > m ? c - m : m - c; acc[j] *= __builtin_amdgcn_exp2f(l2g * (float)dd); }
;             st[mt] = acc; }
;         const bf16x8 p0 = pack_tiles(st[0], st[1]), p1 = pack_tiles(st[2], st[3]);
; #pragma unroll
;         for (int et = 0; et < 4; ++et) { OT[et] = __builtin_amdgcn_mfma_f32_16x16x32_bf16(vt_frag(vT, et, 0, r, q), p0, OT[et], 0, 0, 0);
;             OT[et] = __builtin_amdgcn_mfma_f32_16x16x32_bf16(vt_frag(vT, et, 1, r, q), p1, OT[et], 0, 0, 0); }
	v_mfma_f32_16x16x32_bf16 v[130:133], v[134:137], v[40:43], v[130:133]
	v_subrev_u32_e32 v137, 35, v91
	s_nop 6
	v_pk_mul_f32 v[46:47], v[44:45], v[132:133] op_sel_hi:[0,1]
	v_pk_mul_f32 v[44:45], v[44:45], v[130:131] op_sel_hi:[0,1]
	v_mfma_f32_16x16x32_bf16 v[130:133], v[0:3], v[34:37], 0
	v_mfma_f32_16x16x32_bf16 v[130:133], v[4:7], v[40:43], v[130:133]
	s_nop 7
	v_mul_f32_e32 v95, v89, v130
	v_add_u32_e32 v89, -1, v129
	v_subrev_u32_e32 v130, 50, v91
	v_cndmask_b32_e32 v89, v130, v89, vcc
	v_cvt_f32_u32_e32 v89, v89
	v_cmp_gt_u32_e32 vcc, v93, v112
	v_mul_f32_e32 v89, v85, v89
	v_exp_f32_e32 v89, v89
	s_nop 0
	v_mul_f32_e32 v130, v89, v131
	v_add_u32_e32 v89, -2, v129
	v_subrev_u32_e32 v131, 49, v91
	v_cndmask_b32_e32 v89, v131, v89, vcc
	v_cvt_f32_u32_e32 v89, v89
	v_cmp_gt_u32_e32 vcc, v93, v113
	v_cvt_pk_bf16_f32 v130, v95, v130
	v_mul_f32_e32 v89, v85, v89
	v_exp_f32_e32 v89, v89
	s_nop 0
	v_mul_f32_e32 v131, v89, v132
	v_add_u32_e32 v89, -3, v129
	v_subrev_u32_e32 v132, 48, v91
	v_cndmask_b32_e32 v89, v132, v89, vcc
	v_cvt_f32_u32_e32 v89, v89
	v_cmp_gt_u32_e32 vcc, v93, v114
	v_mul_f32_e32 v89, v85, v89
	v_exp_f32_e32 v89, v89
	s_nop 0
	v_mul_f32_e32 v136, v89, v133
	v_add_u32_e32 v89, -16, v129
	v_cndmask_b32_e32 v89, v137, v89, vcc
	v_cvt_f32_u32_e32 v89, v89
	v_mfma_f32_16x16x32_bf16 v[132:135], v[8:11], v[34:37], 0
	v_cmp_gt_u32_e32 vcc, v93, v115
	v_cvt_pk_bf16_f32 v131, v131, v136
	v_mul_f32_e32 v89, v85, v89
	v_mfma_f32_16x16x32_bf16 v[132:135], v[12:15], v[40:43], v[132:135]
	v_exp_f32_e32 v89, v89
	s_nop 6
	v_mul_f32_e32 v137, v89, v132
	v_subrev_u32_e32 v89, 17, v129
	v_subrev_u32_e32 v132, 34, v91
	v_cndmask_b32_e32 v89, v132, v89, vcc
	v_cvt_f32_u32_e32 v89, v89
	v_cmp_gt_u32_e32 vcc, v93, v116
	v_subrev_u32_e32 v132, 33, v91
	v_mul_f32_e32 v89, v85, v89
	v_exp_f32_e32 v89, v89
	s_nop 0
	v_mul_f32_e32 v138, v89, v133
	v_subrev_u32_e32 v89, 18, v129
	v_cndmask_b32_e32 v89, v132, v89, vcc
	v_cvt_f32_u32_e32 v89, v89
	v_cmp_gt_u32_e32 vcc, v93, v117
	v_subrev_u32_e32 v132, 32, v91
	v_mul_f32_e32 v89, v85, v89
	v_exp_f32_e32 v89, v89
	s_nop 0
	v_mul_f32_e32 v139, v89, v134
	v_subrev_u32_e32 v89, 19, v129
	v_cndmask_b32_e32 v89, v132, v89, vcc
	v_cvt_f32_u32_e32 v89, v89
	v_cmp_gt_u32_e32 vcc, v93, v118
	v_mul_f32_e32 v89, v85, v89
	v_exp_f32_e32 v89, v89
	s_nop 0
	v_mul_f32_e32 v140, v89, v135
	v_subrev_u32_e32 v89, 32, v129
	v_cndmask_b32_e32 v89, v141, v89, vcc
	v_cvt_f32_u32_e32 v89, v89
	v_mfma_f32_16x16x32_bf16 v[132:135], v[16:19], v[34:37], 0
	v_cmp_gt_u32_e32 vcc, v93, v119
	v_mul_f32_e32 v89, v85, v89
	v_mfma_f32_16x16x32_bf16 v[132:135], v[20:23], v[40:43], v[132:135]
	v_exp_f32_e32 v89, v89
	v_mfma_f32_16x16x32_bf16 v[34:37], v[24:27], v[34:37], 0
	v_mfma_f32_16x16x32_bf16 v[34:37], v[28:31], v[40:43], v[34:37]
	s_nop 4
	v_mul_f32_e32 v141, v89, v132
	v_subrev_u32_e32 v89, 33, v129
	v_subrev_u32_e32 v132, 18, v91
	v_cndmask_b32_e32 v89, v132, v89, vcc
	v_cvt_f32_u32_e32 v89, v89
	v_cmp_gt_u32_e32 vcc, v93, v120
	v_subrev_u32_e32 v132, 17, v91
	v_subrev_u32_e32 v40, 48, v129
	v_mul_f32_e32 v89, v85, v89
	v_exp_f32_e32 v89, v89
	v_add_u32_e32 v41, -3, v91
	v_mul_f32_e32 v142, v89, v133
	v_subrev_u32_e32 v89, 34, v129
	v_cndmask_b32_e32 v89, v132, v89, vcc
	v_cvt_f32_u32_e32 v89, v89
	v_cmp_gt_u32_e32 vcc, v93, v121
	v_subrev_u32_e32 v132, 35, v129
	v_cvt_pk_bf16_f32 v133, v139, v140
	v_mul_f32_e32 v89, v85, v89
	v_exp_f32_e32 v89, v89
	s_nop 0
	v_mul_f32_e32 v143, v89, v134
	v_add_u32_e32 v89, -16, v91
	v_cndmask_b32_e32 v132, v89, v132, vcc
	v_cmp_gt_u32_e32 vcc, v93, v122
	v_cvt_f32_u32_e32 v132, v132
	v_cvt_pk_bf16_f32 v134, v141, v142
	v_mul_f32_e32 v132, v85, v132
	v_cndmask_b32_e32 v40, v41, v40, vcc
	v_cvt_f32_u32_e32 v40, v40
	v_cmp_gt_u32_e32 vcc, v93, v123
	v_add_u32_e32 v41, -2, v91
	v_exp_f32_e32 v132, v132
	v_mul_f32_e32 v40, v85, v40
	v_exp_f32_e32 v40, v40
	v_mul_f32_e32 v135, v132, v135
	v_cvt_pk_bf16_f32 v132, v137, v138
	v_mul_f32_e32 v34, v40, v34
	v_subrev_u32_e32 v40, 49, v129
	v_cndmask_b32_e32 v40, v41, v40, vcc
	v_cvt_f32_u32_e32 v40, v40
	v_cmp_gt_u32_e32 vcc, v93, v124
	v_add_u32_e32 v41, -1, v91
	v_cvt_pk_bf16_f32 v135, v143, v135
	v_mul_f32_e32 v40, v85, v40
	v_exp_f32_e32 v40, v40
	s_nop 0
	v_mul_f32_e32 v35, v40, v35
	v_subrev_u32_e32 v40, 50, v129
	v_cndmask_b32_e32 v40, v41, v40, vcc
	v_cvt_f32_u32_e32 v40, v40
	v_cmp_gt_u32_e32 vcc, v93, v125
	v_cvt_pk_bf16_f32 v136, v34, v35
	v_mul_f32_e32 v40, v85, v40
	v_exp_f32_e32 v40, v40
	s_nop 0
	v_mul_f32_e32 v36, v40, v36
	v_subrev_u32_e32 v40, 51, v129
	v_cndmask_b32_e32 v40, v91, v40, vcc
	v_cvt_f32_u32_e32 v40, v40
	v_mul_f32_e32 v40, v85, v40
	v_exp_f32_e32 v40, v40
	s_nop 0
	v_mul_f32_e32 v37, v40, v37
	v_add_u32_e32 v40, v73, v62
	v_cvt_pk_bf16_f32 v137, v36, v37
	ds_read2_b64 v[34:37], v40 offset1:4
	ds_read2_b64 v[40:43], v40 offset0:8 offset1:12
	s_waitcnt lgkmcnt(1)
	v_mfma_f32_16x16x32_bf16 v[34:37], v[34:37], v[130:133], v[56:59]
	s_nop 2
	v_add_u32_e32 v56, v105, v62
	s_waitcnt lgkmcnt(0)
	v_mfma_f32_16x16x32_bf16 v[40:43], v[40:43], v[134:137], v[34:37]
	s_nop 2
	ds_read2_b64 v[34:37], v56 offset1:4
	s_waitcnt lgkmcnt(0)
	v_mfma_f32_16x16x32_bf16 v[34:37], v[34:37], v[130:133], v[52:55]
	s_nop 2
	ds_read2_b64 v[52:55], v56 offset0:8 offset1:12
	v_add_u32_e32 v56, v107, v62
	s_waitcnt lgkmcnt(0)
	v_mfma_f32_16x16x32_bf16 v[34:37], v[52:55], v[134:137], v[34:37]
	ds_read2_b64 v[52:55], v56 offset1:4
	s_waitcnt lgkmcnt(0)
	v_mfma_f32_16x16x32_bf16 v[48:51], v[52:55], v[130:133], v[48:51]
	ds_read2_b64 v[52:55], v56 offset0:8 offset1:12
	s_waitcnt lgkmcnt(0)
; __device__ __forceinline__ float sx(float v, int m, int lane) { return __builtin_bit_cast(float, __builtin_amdgcn_ds_bpermute((lane ^ m) << 2, __builtin_bit_cast(int, v))); }
; __device__ __forceinline__ void retout_item(const bf16_t* hbuf, const float* rot, const float* kvbuf, const float* normg, bf16_t* mixed, LAS bf16_t* vT, int item, int lane) {
;     ...
;         float s = 0.f;
; #pragma unroll
;         for (int et = 0; et < 4; ++et) s += (OT[et][0] + OT[et][1]) + (OT[et][2] + OT[et][3]);
;         s += sx(s, 16, lane); s += sx(s, 32, lane);
;         const float mu = s * (1.0f / 64.0f); float v = 0.f;
; #pragma unroll
;         for (int et = 0; et < 4; ++et)
; #pragma unroll
;             for (int j = 0; j < 4; ++j) { const float d = OT[et][j] - mu; v += d * d; }
;         v += sx(v, 16, lane); v += sx(v, 32, lane);
;         const float rstd = rsqrtf(v * (1.0f / 64.0f) + LN_EPS);
; #pragma unroll
;         for (int et = 0; et < 4; ++et) { const int e = 16 * et + 4 * q;
;             const u32x2 gw = *(const u32x2*)(hbuf + (t0 + c) * INWP + C_RG + h * 64 + e); const f32x4 ng = *(const f32x4*)(normg + h * 64 + e);
	v_mfma_f32_16x16x32_bf16 v[50:53], v[52:55], v[134:137], v[48:51]
	s_nop 4
	v_add_u32_e32 v48, v109, v62
	ds_read2_b64 v[54:57], v48 offset1:4
	v_mov_b32_e32 v49, v37
	s_waitcnt lgkmcnt(0)
	v_mfma_f32_16x16x32_bf16 v[44:47], v[54:57], v[130:133], v[44:47]
	ds_read2_b64 v[54:57], v48 offset0:8 offset1:12
	v_mov_b32_e32 v48, v34
	s_waitcnt lgkmcnt(0)
	v_mfma_f32_16x16x32_bf16 v[130:133], v[54:57], v[134:137], v[44:47]
	s_nop 3
	v_mov_b32_e32 v44, v41
	v_mov_b32_e32 v45, v42
	v_mov_b32_e32 v46, v40
	v_mov_b32_e32 v47, v43
	v_pk_add_f32 v[44:45], v[44:45], v[46:47]
	v_mov_b32_e32 v46, v35
	v_mov_b32_e32 v47, v36
	v_pk_add_f32 v[46:47], v[46:47], v[48:49]
	v_add_f32_e32 v44, v44, v45
	v_pk_add_f32 v[46:47], v[46:47], v[46:47] op_sel:[0,1] op_sel_hi:[1,0]
	v_add_f32_e32 v44, 0, v44
	v_add_f32_e32 v48, v50, v51
	v_add_f32_e32 v54, v52, v53
	v_mov_b32_e32 v45, v130
	v_mov_b32_e32 v47, v131
	v_mov_b32_e32 v49, v132
	v_mov_b32_e32 v55, v133
	v_pk_add_f32 v[44:45], v[44:45], v[46:47]
	v_pk_add_f32 v[46:47], v[48:49], v[54:55]
	s_nop 0
	v_pk_add_f32 v[44:45], v[44:45], v[46:47]
	s_nop 0
	v_add_f32_e32 v44, v44, v45
	ds_bpermute_b32 v45, v69, v44
	s_waitcnt lgkmcnt(0)
	v_add_f32_e32 v44, v44, v45
	ds_bpermute_b32 v45, v71, v44
	s_waitcnt lgkmcnt(0)
	v_add_f32_e32 v45, v44, v45
	v_fmamk_f32 v59, v45, 0xbc800000, v41
	v_fmamk_f32 v55, v45, 0xbc800000, v40
	v_mul_f32_e32 v40, v59, v59
	v_fmac_f32_e32 v40, v55, v55
	v_fmamk_f32 v91, v45, 0xbc800000, v42
	v_fmac_f32_e32 v40, v91, v91
	v_fmac_f32_e32 v43, 0xbc800000, v45
	v_fmac_f32_e32 v40, v43, v43
	v_fmamk_f32 v58, v45, 0xbc800000, v34
	v_fmac_f32_e32 v40, v58, v58
	v_fmamk_f32 v57, v45, 0xbc800000, v35
	v_mul_f32_e32 v44, 0x3c800000, v45
	v_fmac_f32_e32 v40, v57, v57
	v_fmamk_f32 v36, v45, 0xbc800000, v36
	v_fmac_f32_e32 v40, v36, v36
	v_fmac_f32_e32 v37, 0xbc800000, v45
	v_pk_add_f32 v[50:51], v[50:51], v[44:45] op_sel_hi:[1,0] neg_lo:[0,1] neg_hi:[0,1]
	v_fmac_f32_e32 v40, v37, v37
	v_pk_mul_f32 v[34:35], v[50:51], v[50:51]
	v_pk_add_f32 v[48:49], v[52:53], v[44:45] op_sel_hi:[1,0] neg_lo:[0,1] neg_hi:[0,1]
	v_add_f32_e32 v34, v34, v40
	v_add_f32_e32 v40, v35, v34
	v_pk_mul_f32 v[34:35], v[48:49], v[48:49]
	v_pk_add_f32 v[46:47], v[130:131], v[44:45] op_sel_hi:[1,0] neg_lo:[0,1] neg_hi:[0,1]
	v_add_f32_e32 v34, v34, v40
	v_add_f32_e32 v40, v35, v34
	v_pk_mul_f32 v[34:35], v[46:47], v[46:47]
	v_pk_add_f32 v[44:45], v[132:133], v[44:45] op_sel_hi:[1,0] neg_lo:[0,1] neg_hi:[0,1]
	v_add_f32_e32 v34, v34, v40
	v_add_f32_e32 v40, v35, v34
	v_pk_mul_f32 v[34:35], v[44:45], v[44:45]
	v_lshl_add_u64 v[52:53], v[98:99], 0, s[36:37]
	global_load_dwordx2 v[144:145], v[52:53], off offset:-64
	global_load_dwordx4 v[152:155], v[96:97], off
	global_load_dwordx2 v[146:147], v[52:53], off offset:-32
	global_load_dwordx4 v[156:159], v[96:97], off offset:64
	global_load_dwordx2 v[148:149], v[52:53], off
	global_load_dwordx4 v[160:163], v[96:97], off offset:128
	global_load_dwordx2 v[150:151], v[52:53], off offset:32
	global_load_dwordx4 v[172:175], v[96:97], off offset:192
	v_add_f32_e32 v34, v34, v40
	v_add_f32_e32 v34, v35, v34
	ds_bpermute_b32 v35, v69, v34
	v_lshl_add_u64 v[98:99], v[98:99], 0, s[10:11]
	s_waitcnt lgkmcnt(0)
	v_add_f32_e32 v34, v34, v35
	ds_bpermute_b32 v35, v71, v34
	s_waitcnt lgkmcnt(0)
	v_add_f32_e32 v34, v34, v35
	v_fmamk_f32 v34, v34, 0x3c800000, v206
	v_cmp_gt_f32_e32 vcc, s33, v34
	v_mul_f32_e32 v35, 0x4b800000, v34
	s_nop 0
	v_cndmask_b32_e32 v34, v34, v35, vcc
	v_rsq_f32_e32 v34, v34
	s_nop 0
	v_mul_f32_e32 v35, 0x45800000, v34
	v_cndmask_b32_e32 v56, v34, v35, vcc
	v_mul_f32_e32 v41, v55, v56
	v_mul_f32_e32 v55, v91, v56
	v_mul_f32_e32 v43, v43, v56
	v_mov_b32_e32 v91, v89
	s_waitcnt vmcnt(0)
; __device__ __forceinline__ unsigned pk2(float lo, float hi) { unsigned r; asm("v_cvt_pk_bf16_f32 %0, %1, %2" : "=v"(r) : "v"(lo), "v"(hi)); return r; }
; __device__ __forceinline__ float bflo(unsigned u) { return __uint_as_float(u << 16); }
; __device__ __forceinline__ float bfhi(unsigned u) { return __uint_as_float(u & 0xffff0000u); }
; __device__ __forceinline__ float sl(float v, int src) { return __builtin_bit_cast(float, __builtin_amdgcn_ds_bpermute(src << 2, __builtin_bit_cast(int, v))); }
; __device__ __forceinline__ void retout_item(const bf16_t* hbuf, const float* rot, const float* kvbuf, const float* normg, bf16_t* mixed, LAS bf16_t* vT, int item, int lane) {
;     ...
;         for (int et = 0; et < 4; ++et) { const int e = 16 * et + 4 * q;
;             const u32x2 gw = *(const u32x2*)(hbuf + (t0 + c) * INWP + C_RG + h * 64 + e); const f32x4 ng = *(const f32x4*)(normg + h * 64 + e);
;             float gt[4] = {bflo(gw.x), bfhi(gw.x), bflo(gw.y), bfhi(gw.y)}, o[4];
; #pragma unroll
;             for (int j = 0; j < 4; ++j) { const float sl = gt[j] * __builtin_amdgcn_rcpf(1.0f + __expf(-gt[j])); o[j] = (OT[et][j] - mu) * rstd * ng[j] * sl; }
;             u32x2 w; w.x = pk2(o[0], o[1]); w.y = pk2(o[2], o[3]);
;             *(u32x2*)(mixed + (t0 + c) * 1024 + M_RET + h * 64 + e) = w; }
;     }
; __device__ __forceinline__ void run_phase(const Args& a, const int ph, LAS unsigned char* lds, const int tid, const int rpt) {
;     ...
;                 for (int it = gw; it < 12 * NCHUNK; it += NGW) retout_item(hbuf, rot, (const float*)(ws + WS_RPREV), a.in[5] + l * 384, mixed, vT, it, lane);
	v_mov_b32_e32 v34, v144
	v_mov_b32_e32 v35, v145
	v_lshlrev_b32_e32 v40, 16, v34
	v_lshlrev_b32_e32 v54, 16, v35
	v_and_b32_e32 v42, 0xffff0000, v35
	v_mul_f32_e32 v35, 0xbfb8aa3b, v40
	v_exp_f32_e32 v35, v35
	v_and_b32_e32 v34, 0xffff0000, v34
	v_mov_b32_e32 v130, v152
	v_mov_b32_e32 v131, v153
	v_mov_b32_e32 v132, v154
	v_mov_b32_e32 v133, v155
	v_mov_b32_e32 v135, v130
	v_add_f32_e32 v35, 1.0, v35
	v_rcp_f32_e32 v134, v35
	v_mul_f32_e32 v35, 0xbfb8aa3b, v34
	v_exp_f32_e32 v35, v35
	v_pk_mul_f32 v[40:41], v[134:135], v[40:41]
	s_nop 0
	v_mul_f32_e32 v40, v40, v41
	v_add_f32_e32 v35, 1.0, v35
	v_rcp_f32_e32 v130, v35
	v_mul_f32_e32 v35, v59, v56
	v_mul_f32_e32 v135, v36, v56
	v_pk_mul_f32 v[34:35], v[130:131], v[34:35]
	s_nop 0
	v_mul_f32_e32 v41, v34, v35
	v_mul_f32_e32 v34, 0xbfb8aa3b, v54
	v_exp_f32_e32 v34, v34
	v_mov_b32_e32 v35, v132
	v_mul_f32_e32 v131, v58, v56
	v_add_f32_e32 v34, 1.0, v34
	v_rcp_f32_e32 v34, v34
	s_nop 0
	v_pk_mul_f32 v[34:35], v[34:35], v[54:55]
	s_nop 0
	v_mul_f32_e32 v54, v34, v35
	v_mul_f32_e32 v34, 0xbfb8aa3b, v42
	v_exp_f32_e32 v34, v34
	s_nop 0
	v_add_f32_e32 v34, 1.0, v34
	v_rcp_f32_e32 v132, v34
	s_nop 0
	v_pk_mul_f32 v[34:35], v[132:133], v[42:43]
	s_nop 0
	v_mul_f32_e32 v35, v34, v35
	v_cvt_pk_bf16_f32 v35, v54, v35
	v_lshl_add_u64 v[54:55], v[102:103], 0, s[36:37]
	v_cvt_pk_bf16_f32 v34, v40, v41
	global_store_dwordx2 v[54:55], v[34:35], off offset:-64
	s_nop 0
	v_mul_f32_e32 v133, v57, v56
	v_lshl_add_u64 v[102:103], v[102:103], 0, s[20:21]
	v_mov_b32_e32 v34, v146
	v_mov_b32_e32 v35, v147
	v_lshlrev_b32_e32 v130, 16, v34
	v_and_b32_e32 v132, 0xffff0000, v34
	v_lshlrev_b32_e32 v134, 16, v35
	v_and_b32_e32 v34, 0xffff0000, v35
	v_mul_f32_e32 v35, 0xbfb8aa3b, v130
	v_exp_f32_e32 v35, v35
	v_mov_b32_e32 v40, v156
	v_mov_b32_e32 v41, v157
	v_mov_b32_e32 v42, v158
	v_mov_b32_e32 v43, v159
	v_mov_b32_e32 v137, v40
	v_add_f32_e32 v35, 1.0, v35
	v_rcp_f32_e32 v136, v35
	v_mul_f32_e32 v35, 0xbfb8aa3b, v132
	v_exp_f32_e32 v35, v35
	v_pk_mul_f32 v[58:59], v[136:137], v[130:131]
	s_nop 0
	v_mul_f32_e32 v58, v58, v59
	v_add_f32_e32 v35, 1.0, v35
	v_rcp_f32_e32 v40, v35
	v_mul_f32_e32 v35, 0xbfb8aa3b, v134
	v_exp_f32_e32 v35, v35
	v_mul_f32_e32 v59, v51, v56
	v_pk_mul_f32 v[40:41], v[40:41], v[132:133]
	v_mul_f32_e32 v131, v48, v56
	v_add_f32_e32 v35, 1.0, v35
	v_mul_f32_e32 v57, v40, v41
	v_rcp_f32_e32 v40, v35
	v_mul_f32_e32 v35, 0xbfb8aa3b, v34
	v_exp_f32_e32 v35, v35
	v_mov_b32_e32 v41, v42
	v_pk_mul_f32 v[40:41], v[40:41], v[134:135]
	v_mul_f32_e32 v51, v45, v56
	v_add_f32_e32 v35, 1.0, v35
	v_rcp_f32_e32 v42, v35
	v_mul_f32_e32 v35, v37, v56
	v_mul_f32_e32 v36, v40, v41
	v_pk_mul_f32 v[34:35], v[42:43], v[34:35]
	s_nop 0
	v_mul_f32_e32 v35, v34, v35
	v_cvt_pk_bf16_f32 v34, v58, v57
	v_cvt_pk_bf16_f32 v35, v36, v35
	global_store_dwordx2 v[54:55], v[34:35], off offset:-32
	s_nop 0
	v_mul_f32_e32 v43, v50, v56
	v_mov_b32_e32 v40, v148
	v_mov_b32_e32 v41, v149
	v_lshlrev_b32_e32 v42, 16, v40
	v_and_b32_e32 v58, 0xffff0000, v40
	v_lshlrev_b32_e32 v130, 16, v41
	v_and_b32_e32 v40, 0xffff0000, v41
	v_mul_f32_e32 v41, 0xbfb8aa3b, v42
	v_mov_b32_e32 v34, v160
	v_mov_b32_e32 v35, v161
	v_mov_b32_e32 v36, v162
	v_mov_b32_e32 v37, v163
	v_mov_b32_e32 v133, v34
	v_mul_f32_e32 v34, 0xbfb8aa3b, v58
	v_exp_f32_e32 v41, v41
	v_exp_f32_e32 v34, v34
	v_add_f32_e32 v41, 1.0, v41
	v_add_f32_e32 v34, 1.0, v34
	v_rcp_f32_e32 v132, v41
	v_rcp_f32_e32 v34, v34
	v_mul_f32_e32 v41, v49, v56
	v_mul_f32_e32 v49, v44, v56
	v_pk_mul_f32 v[42:43], v[132:133], v[42:43]
	v_pk_mul_f32 v[34:35], v[34:35], v[58:59]
	v_mul_f32_e32 v42, v42, v43
	v_mul_f32_e32 v43, v34, v35
	v_mul_f32_e32 v34, 0xbfb8aa3b, v130
	v_exp_f32_e32 v34, v34
	v_mov_b32_e32 v35, v36
	v_add_f32_e32 v34, 1.0, v34
	v_rcp_f32_e32 v34, v34
	s_nop 0
	v_pk_mul_f32 v[34:35], v[34:35], v[130:131]
	s_nop 0
	v_mul_f32_e32 v48, v34, v35
	v_mul_f32_e32 v34, 0xbfb8aa3b, v40
	v_exp_f32_e32 v34, v34
	s_nop 0
	v_add_f32_e32 v34, 1.0, v34
	v_rcp_f32_e32 v36, v34
	s_nop 0
	v_pk_mul_f32 v[34:35], v[36:37], v[40:41]
	s_nop 0
	v_mul_f32_e32 v35, v34, v35
	v_cvt_pk_bf16_f32 v34, v42, v43
	v_cvt_pk_bf16_f32 v35, v48, v35
	global_store_dwordx2 v[54:55], v[34:35], off
	s_nop 0
	v_mul_f32_e32 v43, v46, v56
	v_mov_b32_e32 v40, v150
	v_mov_b32_e32 v41, v151
	v_lshlrev_b32_e32 v42, 16, v40
	v_and_b32_e32 v40, 0xffff0000, v40
	v_mov_b32_e32 v34, v172
	v_mov_b32_e32 v35, v173
	v_mov_b32_e32 v36, v174
	v_mov_b32_e32 v37, v175
	v_mov_b32_e32 v53, v34
	v_mul_f32_e32 v34, 0xbfb8aa3b, v40
	v_exp_f32_e32 v34, v34
	v_lshlrev_b32_e32 v48, 16, v41
	v_and_b32_e32 v50, 0xffff0000, v41
	v_mul_f32_e32 v41, 0xbfb8aa3b, v42
	v_exp_f32_e32 v41, v41
	v_add_f32_e32 v34, 1.0, v34
	v_rcp_f32_e32 v34, v34
	v_add_f32_e32 v41, 1.0, v41
	v_rcp_f32_e32 v52, v41
	v_mul_f32_e32 v41, v47, v56
	v_pk_mul_f32 v[34:35], v[34:35], v[40:41]
	v_pk_mul_f32 v[42:43], v[52:53], v[42:43]
	v_mul_f32_e32 v40, v34, v35
	v_mul_f32_e32 v34, 0xbfb8aa3b, v48
	v_exp_f32_e32 v34, v34
	v_mov_b32_e32 v35, v36
	v_mul_f32_e32 v42, v42, v43
	v_add_f32_e32 v34, 1.0, v34
	v_rcp_f32_e32 v34, v34
	s_nop 0
	v_pk_mul_f32 v[34:35], v[34:35], v[48:49]
	s_nop 0
	v_mul_f32_e32 v41, v34, v35
	v_mul_f32_e32 v34, 0xbfb8aa3b, v50
	v_exp_f32_e32 v34, v34
	s_nop 0
	v_add_f32_e32 v34, 1.0, v34
	v_rcp_f32_e32 v36, v34
	s_nop 0
	v_pk_mul_f32 v[34:35], v[36:37], v[50:51]
	s_nop 0
	v_mul_f32_e32 v35, v34, v35
	v_cvt_pk_bf16_f32 v34, v42, v40
	v_cvt_pk_bf16_f32 v35, v41, v35
	global_store_dwordx2 v[54:55], v[34:35], off offset:32
	s_cbranch_scc1 .LBB0_176
	s_waitcnt lgkmcnt(0)
	v_readlane_b32 s98, v249, 49
	s_nop 0
	s_cmp_eq_u32 s98, 0x100
	s_cbranch_scc1 .Lsp3b_fast
	s_add_i32 s0, s0, s14
	s_cmpk_gt_i32 s0, 0xbff
	s_cbranch_scc0 .LBB0_175
	s_branch .LBB0_178
.Lsp3b_fast:
	s_cmpk_gt_i32 s0, 0x7ff
	s_cbranch_scc1 .LBB0_178
	v_readlane_b32 s98, v249, 52
	s_nop 0
	s_cmp_gt_u32 s98, 3
	s_cbranch_scc1 .LBB0_178
	v_readlane_b32 s99, v251, 12
	s_nop 0
	s_lshl_b32 s99, s99, 2
	s_add_i32 s0, s98, s99
	s_add_i32 s0, s0, 0x800
	s_branch .LBB0_175

; __device__ __forceinline__ void run_phase(const Args& a, const int ph, LAS unsigned char* lds, const int tid, const int rpt) {
;     ...
;                       for (;;) { int it0 = 0; if (lane == 0) it0 = (int)atomicAdd(qctr, 2u); it0 = nstat + __builtin_amdgcn_readfirstlane(it0); if (it0 >= 12 * 1024) break;
.LBB0_277:
	v_mov_b32_e32 v4, 0
	s_and_saveexec_b64 s[0:1], s[36:37]
	s_cbranch_execz .LBB0_281
	s_mov_b64 s[22:23], exec
	v_mbcnt_lo_u32_b32 v4, s22, 0
	v_mbcnt_hi_u32_b32 v4, s23, v4
	v_cmp_eq_u32_e32 vcc, 0, v4
	s_and_saveexec_b64 s[20:21], vcc
	s_cbranch_execz .LBB0_280
	s_bcnt1_i32_b64 s12, s[22:23]
	v_readlane_b32 s22, v249, 7
	v_mov_b32_e32 v5, s12
	v_readlane_b32 s23, v249, 8
	v_readlane_b32 s98, v249, 49
	s_nop 0
	s_cmp_eq_u32 s98, 0x100
	s_cbranch_scc0 .Lxq_skip_a
	v_readlane_b32 s98, v251, 8
	s_sub_u32 s98, s22, s98
	s_mul_i32 s98, s98, 3
	v_readlane_b32 s99, v251, 37
	s_lshl_b32 s99, s99, 5
	s_add_i32 s98, s98, s99
	s_add_u32 s22, s22, s98
	s_addc_u32 s23, s23, 0
.Lxq_skip_a:
	s_nop 4
	global_atomic_add v5, v33, v5, s[22:23] sc0

; __device__ __forceinline__ void run_phase(const Args& a, const int ph, LAS unsigned char* lds, const int tid, const int rpt) {
;     ...
;                       for (;;) { int it0 = 0; if (lane == 0) it0 = (int)atomicAdd(qctr, 2u); it0 = nstat + __builtin_amdgcn_readfirstlane(it0); if (it0 >= 12 * 1024) break;
.LBB0_281:
	s_or_b64 exec, exec, s[0:1]
	v_readfirstlane_b32 s12, v4
	v_readlane_b32 s98, v249, 49
	s_nop 0
	s_cmp_eq_u32 s98, 0x100
	s_cbranch_scc0 .Lxq_skip_b
	s_cmp_ge_u32 s12, 0x200
	s_cselect_b32 s12, 0x10000, s12
	v_readlane_b32 s98, v251, 37
	s_lshl_b32 s98, s98, 9
	s_add_i32 s12, s12, s98
.Lxq_skip_b:
	v_readlane_b32 s0, v249, 54
	s_add_i32 s12, s12, s0
	s_mov_b64 s[0:1], -1
	s_cmpk_gt_i32 s12, 0x2fff
	s_mov_b32 s15, s12
	s_cbranch_scc0 .LBB0_283
	s_branch .LBB0_276
